# plus NSA: output accumulators kept in place across tiles (32 v_mov_b64 per tile removed); selected-branch score block fast copy without causal mask
# speedup vs baseline: 1.0115x; 1.0115x over previous
.LBB0_733:
	s_or_b64 exec, exec, s[4:5]
	s_add_i32 s74, 0, 0x1e310
	v_mul_f32_e32 v36, v1, v40
	v_mov_b32_e32 v1, s74
	s_waitcnt lgkmcnt(0)
	s_barrier
	ds_read_b32 v1, v1
	s_sub_i32 s0, s78, s2
	s_add_i32 s73, s0, s81
	s_add_i32 s73, s73, 1
	s_movk_i32 s0, 0x200
	s_waitcnt lgkmcnt(0)
	v_readfirstlane_b32 s2, v1
	s_bitcmp0_b32 s2, 8
	s_cselect_b32 s68, 0x100, s0
	s_lshl_b64 s[0:1], s[88:89], 11
	s_lshl_b32 s2, s2, 6
	v_ashrrev_i32_e32 v35, 31, v34
	s_and_b32 s88, s2, 0x3fc0
	v_lshl_add_u64 v[146:147], s[0:1], 0, v[34:35]
	v_readlane_b32 s0, v253, 32
	v_readlane_b32 s2, v253, 34
	v_readlane_b32 s3, v253, 35
	v_pk_mul_f32 v[142:143], v[36:37], v[4:5] op_sel_hi:[0,1]
	v_pk_mul_f32 v[144:145], v[36:37], v[2:3] op_sel_hi:[0,1]
	v_lshl_add_u64 v[2:3], v[146:147], 0, s[88:89]
	v_readlane_b32 s1, v253, 33
	v_mov_b64_e32 v[4:5], s[2:3]
	s_movk_i32 s2, 0x1e00
	v_mad_u64_u32 v[4:5], s[0:1], v2, s2, v[4:5]
	s_mov_b32 s69, 0
	v_mad_i32_i24 v5, v3, s2, v5
	v_lshl_add_u64 v[2:3], v[4:5], 0, s[68:69]
	v_lshlrev_b32_e32 v4, 4, v39
	v_mov_b32_e32 v5, v0
	v_lshl_add_u64 v[2:3], v[2:3], 0, v[4:5]
	s_mov_b64 s[0:1], 0x1900
	v_pk_mul_f32 v[140:141], v[36:37], v[6:7] op_sel_hi:[0,1]
	v_lshl_add_u64 v[6:7], v[2:3], 0, s[0:1]
	v_add_co_u32_e32 v2, vcc, s86, v2
	s_movk_i32 s0, 0x90
	s_nop 0
	v_addc_co_u32_e32 v3, vcc, 0, v3, vcc
	global_load_dwordx4 v[96:99], v[2:3], off offset:2304
	global_load_dwordx4 v[100:103], v[6:7], off offset:128
	v_mul_lo_u32 v1, v34, s0
	s_movk_i32 s0, 0xff72
	v_add_u32_e32 v1, 0, v1
	v_mul_lo_u32 v2, v34, s0
	v_mul_u32_u24_e32 v3, 0x440, v39
	v_pk_mul_f32 v[130:131], v[36:37], v[16:17] op_sel_hi:[0,1]
	v_pk_mul_f32 v[132:133], v[36:37], v[14:15] op_sel_hi:[0,1]
	v_pk_mul_f32 v[134:135], v[36:37], v[12:13] op_sel_hi:[0,1]
	v_pk_mul_f32 v[136:137], v[36:37], v[10:11] op_sel_hi:[0,1]
	v_pk_mul_f32 v[138:139], v[36:37], v[8:9] op_sel_hi:[0,1]
	v_pk_mul_f32 v[114:115], v[36:37], v[32:33] op_sel_hi:[0,1]
	v_pk_mul_f32 v[116:117], v[36:37], v[30:31] op_sel_hi:[0,1]
	v_pk_mul_f32 v[118:119], v[36:37], v[28:29] op_sel_hi:[0,1]
	v_pk_mul_f32 v[120:121], v[36:37], v[26:27] op_sel_hi:[0,1]
	v_pk_mul_f32 v[122:123], v[36:37], v[24:25] op_sel_hi:[0,1]
	v_pk_mul_f32 v[124:125], v[36:37], v[22:23] op_sel_hi:[0,1]
	v_pk_mul_f32 v[126:127], v[36:37], v[20:21] op_sel_hi:[0,1]
	v_pk_mul_f32 v[128:129], v[36:37], v[18:19] op_sel_hi:[0,1]
	v_add_u32_e32 v153, v1, v4
	v_add3_u32 v154, v1, v2, v3
	s_cmp_lt_i32 s73, 1
	v_readlane_b32 s4, v253, 36
	v_readlane_b32 s5, v253, 37
	v_readlane_b32 s6, v253, 38
	v_readlane_b32 s7, v253, 39
	v_readlane_b32 s8, v253, 40
	v_readlane_b32 s9, v253, 41
	v_readlane_b32 s10, v253, 42
	v_readlane_b32 s11, v253, 43
	v_readlane_b32 s12, v253, 44
	v_readlane_b32 s13, v253, 45
	v_readlane_b32 s14, v253, 46
	v_readlane_b32 s15, v253, 47
	s_waitcnt vmcnt(1)
	ds_write_b128 v153, v[96:99]
	s_waitcnt vmcnt(0)
	ds_write_b16 v154, v100 offset:18432
	ds_write_b16_d16_hi v154, v100 offset:18568
	ds_write_b16 v154, v101 offset:18704
	ds_write_b16_d16_hi v154, v101 offset:18840
	ds_write_b16 v154, v102 offset:18976
	ds_write_b16_d16_hi v154, v102 offset:19112
	ds_write_b16 v154, v103 offset:19248
	ds_write_b16_d16_hi v154, v103 offset:19384
	s_waitcnt lgkmcnt(0)
	s_barrier
	s_cbranch_scc1 .LBB0_852
	v_mul_f32_e32 v1, 0xbfb8aa3b, v105
	v_exp_f32_e32 v1, v1
	v_sub_u32_e32 v2, v68, v150
	v_writelane_b32 v254, s41, 25
	v_cmp_gt_i32_e64 s[0:1], 0, v2
	v_add_f32_e32 v1, 1.0, v1
	v_cmp_gt_i32_e64 s[2:3], 35, v2
	v_writelane_b32 v254, s0, 15
	v_rcp_f32_e32 v156, v1
	v_mov_b32_e32 v14, v0
	v_writelane_b32 v254, s1, 16
	v_writelane_b32 v254, s2, 17
	v_mov_b32_e32 v15, v0
	v_lshlrev_b32_e32 v16, 3, v39
	v_writelane_b32 v254, s3, 18
	v_cmp_gt_i32_e64 s[2:3], 8, v2
	v_sub_u32_e32 v155, v150, v67
	v_cmp_gt_i32_e64 s[86:87], 32, v2
	v_cmp_gt_i32_e64 s[94:95], 1, v2
	v_cmp_gt_i32_e64 s[82:83], 33, v2
	v_cmp_gt_i32_e64 s[92:93], 2, v2
	v_cmp_gt_i32_e64 s[96:97], 34, v2
	v_cmp_gt_i32_e64 s[0:1], 3, v2
	v_writelane_b32 v254, s2, 19
	v_cmp_gt_i32_e64 s[20:21], 40, v2
	v_cmp_gt_i32_e64 s[22:23], 9, v2
	v_cmp_gt_i32_e64 s[24:25], 41, v2
	v_cmp_gt_i32_e64 s[26:27], 10, v2
	v_cmp_gt_i32_e64 s[28:29], 42, v2
	v_cmp_gt_i32_e64 s[30:31], 11, v2
	v_cmp_gt_i32_e64 s[34:35], 43, v2
	v_cmp_gt_i32_e64 s[36:37], 16, v2
	v_cmp_gt_i32_e64 s[38:39], 48, v2
	v_cmp_gt_i32_e64 s[40:41], 17, v2
	v_cmp_gt_i32_e64 s[42:43], 49, v2
	v_cmp_gt_i32_e64 s[44:45], 18, v2
	v_cmp_gt_i32_e64 s[46:47], 50, v2
	v_cmp_gt_i32_e64 s[48:49], 19, v2
	v_cmp_gt_i32_e64 s[50:51], 51, v2
	v_cmp_gt_i32_e64 s[52:53], 24, v2
	v_cmp_gt_i32_e64 s[54:55], 56, v2
	v_cmp_gt_i32_e64 s[56:57], 25, v2
	v_cmp_gt_i32_e64 s[58:59], 57, v2
	v_cmp_gt_i32_e64 s[60:61], 26, v2
	v_cmp_gt_i32_e64 s[62:63], 58, v2
	v_cmp_gt_i32_e64 s[64:65], 27, v2
	v_cmp_gt_i32_e64 s[66:67], 59, v2
	v_mul_u32_u24_e32 v158, 0x88, v66
	v_mov_b32_e32 v1, v0
	v_mov_b32_e32 v2, v0
	v_mov_b32_e32 v3, v0
	v_mov_b32_e32 v4, v0
	v_mov_b32_e32 v5, v0
	v_mov_b32_e32 v6, v0
	v_mov_b32_e32 v7, v0
	v_mov_b32_e32 v8, v0
	v_mov_b32_e32 v9, v0
	v_mov_b32_e32 v10, v0
	v_mov_b32_e32 v11, v0
	v_mov_b32_e32 v12, v0
	v_mov_b32_e32 v13, v0
	v_mov_b64_e32 v[78:79], v[14:15]
	v_mov_b64_e32 v[62:63], v[14:15]
	v_mul_u32_u24_e32 v157, 0x90, v37
	v_writelane_b32 v254, s3, 20
	v_mul_u32_u24_e32 v159, 0x88, v37
	v_mov_b32_e32 v161, 0xf149f2ca
	v_mov_b32_e32 v166, 0
	v_lshlrev_b32_e32 v104, 1, v16
	v_mov_b64_e32 v[76:77], v[12:13]
	v_mov_b64_e32 v[74:75], v[10:11]
	v_mov_b64_e32 v[72:73], v[8:9]
	v_mov_b64_e32 v[70:71], v[6:7]
	v_mov_b64_e32 v[68:69], v[4:5]
	v_mov_b64_e32 v[66:67], v[2:3]
	v_mov_b64_e32 v[64:65], v[0:1]
	v_mov_b64_e32 v[60:61], v[12:13]
	v_mov_b64_e32 v[58:59], v[10:11]
	v_mov_b64_e32 v[56:57], v[8:9]
	v_mov_b64_e32 v[54:55], v[6:7]
	v_mov_b64_e32 v[52:53], v[4:5]
	v_mov_b64_e32 v[50:51], v[2:3]
	v_mov_b64_e32 v[48:49], v[0:1]
	v_mov_b32_e32 v16, 0
	v_mov_b32_e32 v17, 0
	v_mov_b32_e32 v18, 0
	v_mov_b32_e32 v19, 0
	v_mov_b32_e32 v20, 0
	v_mov_b32_e32 v21, 0
	v_mov_b32_e32 v22, 0
	v_mov_b32_e32 v23, 0
	v_mov_b32_e32 v24, 0
	v_mov_b32_e32 v25, 0
	v_mov_b32_e32 v26, 0
	v_mov_b32_e32 v27, 0
	v_mov_b32_e32 v28, 0
	v_mov_b32_e32 v29, 0
	v_mov_b32_e32 v30, 0
	v_mov_b32_e32 v31, 0
	v_mov_b32_e32 v32, 0
	v_mov_b32_e32 v33, 0
	v_mov_b32_e32 v34, 0
	v_mov_b32_e32 v35, 0
	v_mov_b32_e32 v36, 0
	v_mov_b32_e32 v37, 0
	v_mov_b32_e32 v38, 0
	v_mov_b32_e32 v39, 0
	v_mov_b32_e32 v40, 0
	v_mov_b32_e32 v41, 0
	v_mov_b32_e32 v42, 0
	v_mov_b32_e32 v43, 0
	v_mov_b32_e32 v44, 0
	v_mov_b32_e32 v45, 0
	v_mov_b32_e32 v46, 0
	v_mov_b32_e32 v47, 0
	s_cmp_lt_i32 s73, 2
	s_cbranch_scc1 .Lnsa_pf_skip
	v_mov_b32_e32 v1, s74
	ds_read_b32 v1, v1 offset:4
	s_movk_i32 s4, 0x200
	s_mov_b32 s91, s89
	v_readlane_b32 s6, v253, 34
	s_waitcnt lgkmcnt(0)
	v_readfirstlane_b32 s68, v1
	s_bitcmp0_b32 s68, 8
	s_cselect_b32 s88, 0x100, s4
	s_lshl_b32 s68, s68, 6
	v_readlane_b32 s7, v253, 35
	s_and_b32 s90, s68, 0x3fc0
	v_lshl_add_u64 v[4:5], v[146:147], 0, s[90:91]
	v_mov_b64_e32 v[2:3], s[6:7]
	s_movk_i32 s4, 0x1e00
	v_mad_u64_u32 v[2:3], s[90:91], v4, s4, v[2:3]
	v_mad_i32_i24 v3, v5, s4, v3
	v_lshl_add_u64 v[2:3], v[2:3], 0, s[88:89]
	v_mov_b32_e32 v105, v0
	v_lshl_add_u64 v[2:3], v[2:3], 0, v[104:105]
	s_mov_b64 s[4:5], 0x1900
	v_lshl_add_u64 v[4:5], v[2:3], 0, s[4:5]
	v_add_co_u32_e32 v2, vcc, 0x1000, v2
	s_nop 1
	v_addc_co_u32_e32 v3, vcc, 0, v3, vcc
	global_load_dwordx4 v[206:209], v[2:3], off offset:2304
	global_load_dwordx4 v[210:213], v[4:5], off offset:128

.LBB0_737:
	s_cmp_lg_u32 s81, s69
	s_cbranch_scc1 .LBB0_739
	v_mov_b32_e32 v1, v166
	s_nop 1
	v_permlane32_swap_b32_e32 v166, v1
	v_add_f32_e32 v1, v166, v1
	v_rcp_f32_e32 v2, v1
	v_cmp_lt_f32_e32 vcc, 0, v1
	v_mov_b32_e32 v14, v0
	v_mov_b32_e32 v15, v0
	v_cndmask_b32_e32 v1, 0, v2, vcc
	v_mul_f32_e32 v2, v156, v1
	v_pk_fma_f32 v[130:131], v[46:47], v[2:3], v[130:131] op_sel_hi:[1,0,1]
	v_pk_fma_f32 v[132:133], v[44:45], v[2:3], v[132:133] op_sel_hi:[1,0,1]
	v_pk_fma_f32 v[134:135], v[42:43], v[2:3], v[134:135] op_sel_hi:[1,0,1]
	v_pk_fma_f32 v[136:137], v[40:41], v[2:3], v[136:137] op_sel_hi:[1,0,1]
	v_pk_fma_f32 v[138:139], v[38:39], v[2:3], v[138:139] op_sel_hi:[1,0,1]
	v_pk_fma_f32 v[140:141], v[36:37], v[2:3], v[140:141] op_sel_hi:[1,0,1]
	v_pk_fma_f32 v[142:143], v[34:35], v[2:3], v[142:143] op_sel_hi:[1,0,1]
	v_pk_fma_f32 v[144:145], v[32:33], v[2:3], v[144:145] op_sel_hi:[1,0,1]
	v_pk_fma_f32 v[114:115], v[30:31], v[2:3], v[114:115] op_sel_hi:[1,0,1]
	v_pk_fma_f32 v[116:117], v[28:29], v[2:3], v[116:117] op_sel_hi:[1,0,1]
	v_pk_fma_f32 v[118:119], v[26:27], v[2:3], v[118:119] op_sel_hi:[1,0,1]
	v_pk_fma_f32 v[120:121], v[24:25], v[2:3], v[120:121] op_sel_hi:[1,0,1]
	v_pk_fma_f32 v[122:123], v[22:23], v[2:3], v[122:123] op_sel_hi:[1,0,1]
	v_pk_fma_f32 v[124:125], v[20:21], v[2:3], v[124:125] op_sel_hi:[1,0,1]
	v_pk_fma_f32 v[126:127], v[18:19], v[2:3], v[126:127] op_sel_hi:[1,0,1]
	v_pk_fma_f32 v[128:129], v[16:17], v[2:3], v[128:129] op_sel_hi:[1,0,1]
	v_mov_b32_e32 v1, v0
	v_mov_b32_e32 v2, v0
	v_mov_b32_e32 v3, v0
	v_mov_b32_e32 v4, v0
	v_mov_b32_e32 v5, v0
	v_mov_b32_e32 v6, v0
	v_mov_b32_e32 v7, v0
	v_mov_b32_e32 v8, v0
	v_mov_b32_e32 v9, v0
	v_mov_b32_e32 v10, v0
	v_mov_b32_e32 v11, v0
	v_mov_b32_e32 v12, v0
	v_mov_b32_e32 v13, v0
	v_mov_b64_e32 v[30:31], v[14:15]
	v_mov_b64_e32 v[46:47], v[14:15]
	v_mov_b32_e32 v105, 0
	v_mov_b32_e32 v160, 0xf149f2ca
	v_mov_b64_e32 v[28:29], v[12:13]
	v_mov_b64_e32 v[26:27], v[10:11]
	v_mov_b64_e32 v[24:25], v[8:9]
	v_mov_b64_e32 v[22:23], v[6:7]
	v_mov_b64_e32 v[20:21], v[4:5]
	v_mov_b64_e32 v[18:19], v[2:3]
	v_mov_b64_e32 v[16:17], v[0:1]
	v_mov_b64_e32 v[44:45], v[12:13]
	v_mov_b64_e32 v[42:43], v[10:11]
	v_mov_b64_e32 v[40:41], v[8:9]
	v_mov_b64_e32 v[38:39], v[6:7]
	v_mov_b64_e32 v[36:37], v[4:5]
	v_mov_b64_e32 v[34:35], v[2:3]
	v_mov_b64_e32 v[32:33], v[0:1]
	s_branch .LBB0_740
.LBB0_739:
	v_mov_b32_e32 v160, v161
	v_mov_b32_e32 v105, v166

.LBB0_837:
	v_max_f32_e32 v2, v3, v3
	v_max_f32_e32 v48, v4, v4
	v_max_f32_e32 v2, v48, v2
	v_max_f32_e32 v48, v5, v5
	v_max_f32_e32 v49, v6, v6
	v_max_f32_e32 v48, v49, v48
	s_mov_b32 s4, 0xff800000
	v_max3_f32 v2, v2, s4, v48
	v_max_f32_e32 v48, v7, v7
	v_max_f32_e32 v49, v8, v8
	v_max_f32_e32 v48, v49, v48
	v_max_f32_e32 v49, v10, v10
	v_max_f32_e32 v50, v9, v9
	v_max_f32_e32 v49, v50, v49
	v_max3_f32 v2, v2, v48, v49
	v_max_f32_e32 v48, v11, v11
	v_max_f32_e32 v49, v12, v12
	v_max_f32_e32 v48, v49, v48
	v_max_f32_e32 v49, v13, v13
	v_max_f32_e32 v50, v14, v14
	v_max_f32_e32 v49, v50, v49
	v_max3_f32 v2, v2, v48, v49
	v_max_f32_e32 v48, v15, v15
	v_max_f32_e32 v49, v166, v166
	v_max_f32_e32 v48, v49, v48
	v_max_f32_e32 v49, v167, v167
	v_max_f32_e32 v50, v168, v168
	v_max_f32_e32 v49, v50, v49
	v_max3_f32 v2, v2, v48, v49
	v_max_f32_e32 v48, v169, v169
	v_max_f32_e32 v49, v170, v170
	v_max_f32_e32 v48, v49, v48
	v_max_f32_e32 v49, v171, v171
	v_max_f32_e32 v50, v172, v172
	v_max_f32_e32 v49, v50, v49
	v_max3_f32 v2, v2, v48, v49
	v_max_f32_e32 v48, v174, v174
	v_max_f32_e32 v49, v175, v175
	v_max_f32_e32 v48, v49, v48
	v_max_f32_e32 v49, v176, v176
	v_max_f32_e32 v50, v179, v179
	v_max_f32_e32 v49, v50, v49
	v_max3_f32 v2, v2, v48, v49
	v_max_f32_e32 v48, v173, v173
	v_max_f32_e32 v49, v178, v178
	v_max_f32_e32 v48, v49, v48
	v_max_f32_e32 v49, v177, v177
	v_max_f32_e32 v50, v181, v181
	v_max_f32_e32 v49, v50, v49
	v_max3_f32 v2, v2, v48, v49
	v_max_f32_e32 v48, v180, v180
	v_max_f32_e32 v49, v198, v198
	v_max_f32_e32 v48, v49, v48
	v_max_f32_e32 v49, v197, v197
	v_max_f32_e32 v50, v199, v199
	v_max_f32_e32 v49, v50, v49
	v_max3_f32 v2, v2, v48, v49
	v_mov_b32_e32 v48, v2
	s_nop 1
	v_permlane32_swap_b32_e32 v2, v48
	v_max3_f32 v161, v160, v2, v48
	v_sub_f32_e32 v2, v160, v161
	v_exp_f32_e32 v2, v2
	v_cmp_neq_f32_e32 vcc, 1.0, v2
	s_cbranch_vccz .LBB0_839
	v_pk_mul_f32 v[46:47], v[46:47], v[2:3] op_sel_hi:[1,0]
	v_pk_mul_f32 v[44:45], v[44:45], v[2:3] op_sel_hi:[1,0]
	v_pk_mul_f32 v[42:43], v[42:43], v[2:3] op_sel_hi:[1,0]
	v_pk_mul_f32 v[40:41], v[40:41], v[2:3] op_sel_hi:[1,0]
	v_pk_mul_f32 v[38:39], v[38:39], v[2:3] op_sel_hi:[1,0]
	v_pk_mul_f32 v[36:37], v[36:37], v[2:3] op_sel_hi:[1,0]
	v_pk_mul_f32 v[34:35], v[34:35], v[2:3] op_sel_hi:[1,0]
	v_pk_mul_f32 v[32:33], v[32:33], v[2:3] op_sel_hi:[1,0]
	v_pk_mul_f32 v[30:31], v[30:31], v[2:3] op_sel_hi:[1,0]
	v_pk_mul_f32 v[28:29], v[28:29], v[2:3] op_sel_hi:[1,0]
	v_pk_mul_f32 v[26:27], v[26:27], v[2:3] op_sel_hi:[1,0]
	v_pk_mul_f32 v[24:25], v[24:25], v[2:3] op_sel_hi:[1,0]
	v_pk_mul_f32 v[22:23], v[22:23], v[2:3] op_sel_hi:[1,0]
	v_pk_mul_f32 v[20:21], v[20:21], v[2:3] op_sel_hi:[1,0]
	v_pk_mul_f32 v[18:19], v[18:19], v[2:3] op_sel_hi:[1,0]
	v_pk_mul_f32 v[16:17], v[16:17], v[2:3] op_sel_hi:[1,0]
.LBB0_839:
	v_sub_f32_e32 v4, v4, v161
	v_exp_f32_e32 v186, v4
	v_sub_f32_e32 v4, v6, v161
	v_sub_f32_e32 v6, v8, v161
	v_exp_f32_e32 v193, v6
	v_sub_f32_e32 v6, v7, v161
	v_exp_f32_e32 v195, v6
	v_sub_f32_e32 v6, v9, v161
	v_exp_f32_e32 v9, v6
	v_sub_f32_e32 v6, v10, v161
	v_exp_f32_e32 v200, v6
	v_sub_f32_e32 v6, v12, v161
	v_sub_f32_e32 v3, v3, v161
	v_exp_f32_e32 v10, v6
	v_sub_f32_e32 v6, v11, v161
	v_exp_f32_e32 v3, v3
	v_exp_f32_e32 v187, v4
	v_sub_f32_e32 v4, v5, v161
	v_exp_f32_e32 v201, v6
	v_sub_f32_e32 v6, v14, v161
	v_exp_f32_e32 v192, v4
	v_exp_f32_e32 v11, v6
	v_sub_f32_e32 v6, v13, v161
	v_exp_f32_e32 v202, v6
	v_sub_f32_e32 v6, v166, v161
	v_exp_f32_e32 v12, v6
	v_sub_f32_e32 v6, v15, v161
	v_add_f32_e32 v4, v186, v3
	v_exp_f32_e32 v166, v6
	v_sub_f32_e32 v6, v168, v161
	v_add_f32_e32 v4, 0, v4
	v_add_f32_e32 v5, v187, v192
	v_exp_f32_e32 v13, v6
	v_sub_f32_e32 v6, v167, v161
	v_add_f32_e32 v4, v5, v4
	v_add_f32_e32 v5, v193, v195
	v_exp_f32_e32 v167, v6
	v_sub_f32_e32 v6, v170, v161
	v_add_f32_e32 v4, v5, v4
	v_add_f32_e32 v5, v9, v200
	v_exp_f32_e32 v168, v6
	v_sub_f32_e32 v6, v169, v161
	v_add_f32_e32 v4, v5, v4
	v_add_f32_e32 v5, v10, v201
	v_exp_f32_e32 v169, v6
	v_add_f32_e32 v4, v5, v4
	v_add_f32_e32 v5, v11, v202
	v_add_f32_e32 v4, v5, v4
	v_add_f32_e32 v5, v12, v166
	v_add_f32_e32 v4, v5, v4
	v_add_f32_e32 v5, v13, v167
	v_add_f32_e32 v4, v5, v4
	v_add_f32_e32 v5, v168, v169
	v_sub_f32_e32 v6, v172, v161
	v_add_f32_e32 v172, v5, v4
	v_sub_f32_e32 v4, v175, v161
	v_exp_f32_e32 v175, v4
	v_sub_f32_e32 v4, v174, v161
	v_exp_f32_e32 v174, v4
	v_sub_f32_e32 v4, v179, v161
	v_add_u32_e32 v14, s88, v151
	v_exp_f32_e32 v179, v4
	v_add_u32_e32 v4, v14, v158
	v_exp_f32_e32 v170, v6
	v_sub_f32_e32 v6, v171, v161
	v_add_u32_e32 v204, 0x4800, v4
	v_exp_f32_e32 v171, v6
	ds_read2_b64 v[4:7], v204 offset1:2
	v_cvt_pk_bf16_f32 v10, v10, v11
	v_cvt_pk_bf16_f32 v11, v12, v13
	v_add_u32_e32 v12, v14, v159
	v_cvt_pk_bf16_f32 v8, v186, v187
	v_add_u32_e32 v186, 0x4800, v12
	ds_read2_b64 v[12:15], v186 offset1:2
	v_cvt_pk_bf16_f32 v9, v193, v9
	v_sub_f32_e32 v176, v176, v161
	v_add_f32_e32 v203, v170, v171
	s_waitcnt lgkmcnt(1)
	v_mfma_f32_32x32x16_bf16 v[32:47], v[4:7], v[8:11], v[32:47]
	v_sub_f32_e32 v4, v178, v161
	v_exp_f32_e32 v178, v4
	v_sub_f32_e32 v4, v181, v161
	v_exp_f32_e32 v181, v4
	v_sub_f32_e32 v4, v198, v161
	v_exp_f32_e32 v187, v4
	ds_read2_b64 v[4:7], v204 offset0:4 offset1:6
	s_waitcnt lgkmcnt(1)
	v_mfma_f32_32x32x16_bf16 v[16:31], v[12:15], v[8:11], v[16:31]
	v_sub_f32_e32 v8, v199, v161
	v_exp_f32_e32 v193, v8
	ds_read2_b64 v[8:11], v186 offset0:4 offset1:6
	v_cvt_pk_bf16_f32 v12, v168, v170
	v_exp_f32_e32 v168, v176
	v_cvt_pk_bf16_f32 v13, v175, v179
	v_cvt_pk_bf16_f32 v14, v178, v181
	v_cvt_pk_bf16_f32 v15, v187, v193
	s_waitcnt lgkmcnt(1)
	s_nop 0
	v_mfma_f32_32x32x16_bf16 v[32:47], v[4:7], v[12:15], v[32:47]
	v_add_f32_e32 v4, v203, v172
	v_add_f32_e32 v5, v175, v174
	v_add_f32_e32 v4, v5, v4
	v_add_f32_e32 v5, v179, v168
	v_add_f32_e32 v170, v5, v4
	ds_read2_b64 v[4:7], v204 offset0:8 offset1:10
	s_waitcnt lgkmcnt(1)
	v_mfma_f32_32x32x16_bf16 v[16:31], v[8:11], v[12:15], v[16:31]
	ds_read2_b64 v[12:15], v186 offset0:8 offset1:10
	v_sub_f32_e32 v8, v173, v161
	v_exp_f32_e32 v172, v8
	v_cvt_pk_bf16_f32 v8, v3, v192
	v_cvt_pk_bf16_f32 v9, v195, v200
	v_cvt_pk_bf16_f32 v10, v201, v202
	v_cvt_pk_bf16_f32 v11, v166, v167
	v_add_f32_e32 v3, v178, v172
	v_add_f32_e32 v3, v3, v170
	s_waitcnt lgkmcnt(1)
	v_mfma_f32_32x32x16_bf16 v[32:47], v[4:7], v[8:11], v[32:47]
	v_sub_f32_e32 v4, v177, v161
	v_exp_f32_e32 v166, v4
	v_sub_f32_e32 v4, v180, v161
	v_exp_f32_e32 v167, v4
	ds_read2_b64 v[4:7], v204 offset0:12 offset1:14
	s_waitcnt lgkmcnt(1)
	v_mfma_f32_32x32x16_bf16 v[16:31], v[12:15], v[8:11], v[16:31]
	ds_read2_b64 v[12:15], v186 offset0:12 offset1:14
	v_sub_f32_e32 v8, v197, v161
	v_exp_f32_e32 v170, v8
	v_cvt_pk_bf16_f32 v8, v169, v171
	v_cvt_pk_bf16_f32 v9, v174, v168
	v_cvt_pk_bf16_f32 v10, v172, v166
	v_cvt_pk_bf16_f32 v11, v167, v170
	s_waitcnt lgkmcnt(1)
	s_nop 0
	v_mfma_f32_32x32x16_bf16 v[32:47], v[4:7], v[8:11], v[32:47]
	v_add_f32_e32 v4, v181, v166
	v_add_f32_e32 v3, v4, v3
	v_add_f32_e32 v4, v187, v167
	v_add_f32_e32 v3, v4, v3
	v_add_f32_e32 v4, v193, v170
	v_add_f32_e32 v166, v4, v3
	v_fmac_f32_e32 v166, v105, v2
	s_waitcnt lgkmcnt(0)
	v_mfma_f32_32x32x16_bf16 v[16:31], v[12:15], v[8:11], v[16:31]

.LBB0_844:
	s_and_b64 vcc, exec, s[68:69]
	s_cbranch_vccz .LBB0_840
	v_lshrrev_b32_e32 v2, s90, v152
	v_and_b32_e32 v2, 1, v2
	v_cmp_eq_u32_e64 s[68:69], 1, v2
	v_bfe_u32 v2, v152, s90, 1
	v_cmp_ne_u32_e32 vcc, 0, v2
	s_cbranch_vccz .LBB0_849
	v_add3_u32 v14, s91, v148, v107
	v_add3_u32 v15, s91, v157, v107
	ds_read_b128 v[2:5], v14
	ds_read_b128 v[6:9], v14 offset:32
	ds_read_b128 v[10:13], v14 offset:64
	ds_read_b128 v[166:169], v14 offset:96
	ds_read_b128 v[170:173], v15
	ds_read_b128 v[174:177], v15 offset:32
	ds_read_b128 v[178:181], v15 offset:64
	s_cmp_eq_u32 s90, s78
	v_readlane_b32 s4, v254, 15
	v_readlane_b32 s5, v254, 16
	s_waitcnt lgkmcnt(6)
	v_mfma_f32_32x32x16_bf16 v[48:63], v[2:5], v[88:91], 0
	ds_read_b128 v[2:5], v15 offset:96
	s_waitcnt lgkmcnt(6)
	v_mfma_f32_32x32x16_bf16 v[48:63], v[6:9], v[80:83], v[48:63]
	s_waitcnt lgkmcnt(5)
	v_mfma_f32_32x32x16_bf16 v[48:63], v[10:13], v[84:87], v[48:63]
	s_waitcnt lgkmcnt(4)
	v_mfma_f32_32x32x16_bf16 v[48:63], v[166:169], v[92:95], v[48:63]
	s_waitcnt lgkmcnt(3)
	v_mfma_f32_32x32x16_bf16 v[64:79], v[170:173], v[88:91], 0
	s_waitcnt lgkmcnt(2)
	v_mfma_f32_32x32x16_bf16 v[64:79], v[174:177], v[80:83], v[64:79]
	s_waitcnt lgkmcnt(1)
	v_mfma_f32_32x32x16_bf16 v[64:79], v[178:181], v[84:87], v[64:79]
	s_cselect_b64 s[90:91], -1, 0
	s_and_b64 vcc, s[90:91], s[4:5]
	s_mov_b32 s4, 0xff800000
	s_waitcnt lgkmcnt(0)
	v_mfma_f32_32x32x16_bf16 v[64:79], v[2:5], v[92:95], v[64:79]
	s_cmp_eq_u64 s[90:91], 0
	s_cbranch_scc1 .Lsel_fast
	v_fmamk_f32 v7, v149, 0x42000000, v1
	v_add_f32_e32 v6, 0, v1
	s_nop 0
	v_fmac_f32_e32 v6, 0x3e38aa3b, v48
	v_cndmask_b32_e32 v2, v6, v194, vcc
	s_and_b64 vcc, s[90:91], s[86:87]
	v_fmamk_f32 v4, v149, 0x42040000, v1
	v_fmamk_f32 v5, v149, 0x420c0000, v1
	s_nop 7
	v_fmac_f32_e32 v7, 0x3e38aa3b, v64
	v_cndmask_b32_e32 v3, v7, v194, vcc
	v_cndmask_b32_e64 v6, v194, v3, s[68:69]
	v_add_f32_e32 v3, v149, v1
	v_fmac_f32_e32 v3, 0x3e38aa3b, v49
	s_and_b64 vcc, s[90:91], s[94:95]
	v_fmac_f32_e32 v4, 0x3e38aa3b, v65
	v_cndmask_b32_e32 v3, v3, v194, vcc
	s_and_b64 vcc, s[90:91], s[82:83]
	v_cndmask_b32_e32 v4, v4, v194, vcc
	v_cndmask_b32_e64 v7, v194, v2, s[68:69]
	v_cndmask_b32_e64 v9, v194, v3, s[68:69]
	v_cndmask_b32_e64 v8, v194, v4, s[68:69]
	v_max_f32_e32 v2, v7, v6
	v_max_f32_e32 v3, v9, v8
	v_max3_f32 v2, v2, s4, v3
	v_fma_f32 v3, 2.0, v149, v1
	v_fmac_f32_e32 v3, 0x3e38aa3b, v50
	v_fmamk_f32 v4, v149, 0x42080000, v1
	s_and_b64 vcc, s[90:91], s[92:93]
	v_fmac_f32_e32 v4, 0x3e38aa3b, v66
	v_cndmask_b32_e32 v3, v3, v194, vcc
	s_and_b64 vcc, s[90:91], s[96:97]
	v_cndmask_b32_e32 v4, v4, v194, vcc
	v_cndmask_b32_e64 v10, v194, v4, s[68:69]
	v_fmamk_f32 v4, v149, 0x40400000, v1
	v_readlane_b32 s4, v254, 17
	v_fmac_f32_e32 v4, 0x3e38aa3b, v51
	s_and_b64 vcc, s[90:91], s[0:1]
	v_readlane_b32 s5, v254, 18
	v_fmac_f32_e32 v5, 0x3e38aa3b, v67
	v_cndmask_b32_e32 v4, v4, v194, vcc
	s_and_b64 vcc, s[90:91], s[4:5]
	v_cndmask_b32_e32 v5, v5, v194, vcc
	v_cndmask_b32_e64 v11, v194, v3, s[68:69]
	v_cndmask_b32_e64 v14, v194, v4, s[68:69]
	v_cndmask_b32_e64 v12, v194, v5, s[68:69]
	v_max_f32_e32 v3, v11, v10
	v_max_f32_e32 v4, v14, v12
	v_readlane_b32 s4, v254, 19
	v_max3_f32 v2, v2, v3, v4
	v_fmamk_f32 v3, v149, 0x41000000, v1
	v_readlane_b32 s5, v254, 20
	v_fmac_f32_e32 v3, 0x3e38aa3b, v52
	v_fmamk_f32 v4, v149, 0x42200000, v1
	s_and_b64 vcc, s[90:91], s[4:5]
	v_fmac_f32_e32 v4, 0x3e38aa3b, v68
	v_cndmask_b32_e32 v3, v3, v194, vcc
	s_and_b64 vcc, s[90:91], s[20:21]
	v_cndmask_b32_e32 v4, v4, v194, vcc
	v_cndmask_b32_e64 v15, v194, v4, s[68:69]
	v_fmamk_f32 v4, v149, 0x41100000, v1
	v_fmac_f32_e32 v4, 0x3e38aa3b, v53
	v_fmamk_f32 v5, v149, 0x42240000, v1
	s_and_b64 vcc, s[90:91], s[22:23]
	v_fmac_f32_e32 v5, 0x3e38aa3b, v69
	v_cndmask_b32_e32 v4, v4, v194, vcc
	s_and_b64 vcc, s[90:91], s[24:25]
	v_cndmask_b32_e32 v5, v5, v194, vcc
	v_cndmask_b32_e64 v48, v194, v3, s[68:69]
	v_cndmask_b32_e64 v52, v194, v4, s[68:69]
	v_cndmask_b32_e64 v51, v194, v5, s[68:69]
	v_max_f32_e32 v3, v48, v15
	v_max_f32_e32 v4, v52, v51
	v_max3_f32 v2, v2, v3, v4
	v_fmamk_f32 v3, v149, 0x41200000, v1
	v_fmac_f32_e32 v3, 0x3e38aa3b, v54
	v_fmamk_f32 v4, v149, 0x42280000, v1
	s_and_b64 vcc, s[90:91], s[26:27]
	v_fmac_f32_e32 v4, 0x3e38aa3b, v70
	v_cndmask_b32_e32 v3, v3, v194, vcc
	s_and_b64 vcc, s[90:91], s[28:29]
	v_cndmask_b32_e32 v4, v4, v194, vcc
	v_cndmask_b32_e64 v53, v194, v4, s[68:69]
	v_fmamk_f32 v4, v149, 0x41300000, v1
	v_fmac_f32_e32 v4, 0x3e38aa3b, v55
	v_fmamk_f32 v5, v149, 0x422c0000, v1
	s_and_b64 vcc, s[90:91], s[30:31]
	v_fmac_f32_e32 v5, 0x3e38aa3b, v71
	v_cndmask_b32_e32 v4, v4, v194, vcc
	s_and_b64 vcc, s[90:91], s[34:35]
	v_cndmask_b32_e32 v5, v5, v194, vcc
	v_cndmask_b32_e64 v54, v194, v3, s[68:69]
	v_cndmask_b32_e64 v65, v194, v4, s[68:69]
	v_cndmask_b32_e64 v64, v194, v5, s[68:69]
	v_max_f32_e32 v3, v54, v53
	v_max_f32_e32 v4, v65, v64
	v_max3_f32 v2, v2, v3, v4
	v_fmamk_f32 v3, v149, 0x41800000, v1
	v_fmac_f32_e32 v3, 0x3e38aa3b, v56
	v_fmamk_f32 v4, v149, 0x42400000, v1
	s_and_b64 vcc, s[90:91], s[36:37]
	v_fmac_f32_e32 v4, 0x3e38aa3b, v72
	v_cndmask_b32_e32 v3, v3, v194, vcc
	s_and_b64 vcc, s[90:91], s[38:39]
	v_cndmask_b32_e32 v4, v4, v194, vcc
	v_cndmask_b32_e64 v66, v194, v4, s[68:69]
	v_fmamk_f32 v4, v149, 0x41880000, v1
	v_fmac_f32_e32 v4, 0x3e38aa3b, v57
	v_fmamk_f32 v5, v149, 0x42440000, v1
	s_and_b64 vcc, s[90:91], s[40:41]
	v_fmac_f32_e32 v5, 0x3e38aa3b, v73
	v_cndmask_b32_e32 v4, v4, v194, vcc
	s_and_b64 vcc, s[90:91], s[42:43]
	v_cndmask_b32_e32 v5, v5, v194, vcc
	v_cndmask_b32_e64 v67, v194, v3, s[68:69]
	v_cndmask_b32_e64 v68, v194, v4, s[68:69]
	v_cndmask_b32_e64 v57, v194, v5, s[68:69]
	v_max_f32_e32 v3, v67, v66
	v_max_f32_e32 v4, v68, v57
	v_max3_f32 v2, v2, v3, v4
	v_fmamk_f32 v3, v149, 0x41900000, v1
	v_fmac_f32_e32 v3, 0x3e38aa3b, v58
	v_fmamk_f32 v4, v149, 0x42480000, v1
	s_and_b64 vcc, s[90:91], s[44:45]
	v_fmac_f32_e32 v4, 0x3e38aa3b, v74
	v_cndmask_b32_e32 v3, v3, v194, vcc
	s_and_b64 vcc, s[90:91], s[46:47]
	v_cndmask_b32_e32 v4, v4, v194, vcc
	v_cndmask_b32_e64 v58, v194, v4, s[68:69]
	v_fmamk_f32 v4, v149, 0x41980000, v1
	v_fmac_f32_e32 v4, 0x3e38aa3b, v59
	v_fmamk_f32 v5, v149, 0x424c0000, v1
	s_and_b64 vcc, s[90:91], s[48:49]
	v_fmac_f32_e32 v5, 0x3e38aa3b, v75
	v_cndmask_b32_e32 v4, v4, v194, vcc
	s_and_b64 vcc, s[90:91], s[50:51]
	v_cndmask_b32_e32 v5, v5, v194, vcc
	v_cndmask_b32_e64 v69, v194, v3, s[68:69]
	v_cndmask_b32_e64 v59, v194, v4, s[68:69]
	v_cndmask_b32_e64 v49, v194, v5, s[68:69]
	v_max_f32_e32 v3, v69, v58
	v_max_f32_e32 v4, v59, v49
	v_max3_f32 v2, v2, v3, v4
	v_fmamk_f32 v3, v149, 0x41c00000, v1
	v_fmac_f32_e32 v3, 0x3e38aa3b, v60
	s_and_b64 vcc, s[90:91], s[52:53]
	v_fmamk_f32 v4, v149, 0x42600000, v1
	v_cndmask_b32_e32 v3, v3, v194, vcc
	v_fmac_f32_e32 v4, 0x3e38aa3b, v76
	s_and_b64 vcc, s[90:91], s[54:55]
	v_cndmask_b32_e64 v13, v194, v3, s[68:69]
	v_fmamk_f32 v3, v149, 0x41c80000, v1
	v_cndmask_b32_e32 v4, v4, v194, vcc
	v_fmac_f32_e32 v3, 0x3e38aa3b, v61
	v_fmamk_f32 v50, v149, 0x42640000, v1
	s_and_b64 vcc, s[90:91], s[56:57]
	v_fmac_f32_e32 v50, 0x3e38aa3b, v77
	v_cndmask_b32_e32 v3, v3, v194, vcc
	s_and_b64 vcc, s[90:91], s[58:59]
	v_cndmask_b32_e32 v55, v50, v194, vcc
	v_cndmask_b32_e64 v4, v194, v4, s[68:69]
	v_cndmask_b32_e64 v50, v194, v3, s[68:69]
	v_cndmask_b32_e64 v3, v194, v55, s[68:69]
	v_max_f32_e32 v5, v13, v4
	v_max_f32_e32 v55, v50, v3
	v_max3_f32 v2, v2, v5, v55
	v_fmamk_f32 v5, v149, 0x41d00000, v1
	v_fmac_f32_e32 v5, 0x3e38aa3b, v62
	v_fmamk_f32 v55, v149, 0x42680000, v1
	s_and_b64 vcc, s[90:91], s[60:61]
	v_fmac_f32_e32 v55, 0x3e38aa3b, v78
	v_cndmask_b32_e32 v5, v5, v194, vcc
	s_and_b64 vcc, s[90:91], s[62:63]
	v_cndmask_b32_e32 v56, v55, v194, vcc
	v_cndmask_b32_e64 v55, v194, v5, s[68:69]
	v_cndmask_b32_e64 v5, v194, v56, s[68:69]
	v_fmamk_f32 v56, v149, 0x41d80000, v1
	v_fmac_f32_e32 v56, 0x3e38aa3b, v63
	v_fmac_f32_e32 v1, 0x426c0000, v149
	s_and_b64 vcc, s[90:91], s[64:65]
	v_fmac_f32_e32 v1, 0x3e38aa3b, v79
	v_cndmask_b32_e32 v56, v56, v194, vcc
	s_and_b64 vcc, s[90:91], s[66:67]
	v_cndmask_b32_e32 v1, v1, v194, vcc
	v_cndmask_b32_e64 v56, v194, v56, s[68:69]
	v_cndmask_b32_e64 v1, v194, v1, s[68:69]
.Lsel_join:
	v_max_f32_e32 v60, v55, v5
	v_max_f32_e32 v61, v56, v1
	v_max3_f32 v2, v2, v60, v61
	v_mov_b32_e32 v60, v2
	s_nop 1
	v_permlane32_swap_b32_e32 v2, v60
	v_max3_f32 v161, v160, v2, v60
	v_sub_f32_e32 v2, v160, v161
	v_exp_f32_e32 v2, v2
	s_nop 0
	v_cmp_neq_f32_e32 vcc, 1.0, v2
	s_cbranch_vccz .LBB0_848
	v_pk_mul_f32 v[46:47], v[46:47], v[2:3] op_sel_hi:[1,0]
	v_pk_mul_f32 v[44:45], v[44:45], v[2:3] op_sel_hi:[1,0]
	v_pk_mul_f32 v[42:43], v[42:43], v[2:3] op_sel_hi:[1,0]
	v_pk_mul_f32 v[40:41], v[40:41], v[2:3] op_sel_hi:[1,0]
	v_pk_mul_f32 v[38:39], v[38:39], v[2:3] op_sel_hi:[1,0]
	v_pk_mul_f32 v[36:37], v[36:37], v[2:3] op_sel_hi:[1,0]
	v_pk_mul_f32 v[34:35], v[34:35], v[2:3] op_sel_hi:[1,0]
	v_pk_mul_f32 v[32:33], v[32:33], v[2:3] op_sel_hi:[1,0]
	v_pk_mul_f32 v[30:31], v[30:31], v[2:3] op_sel_hi:[1,0]
	v_pk_mul_f32 v[28:29], v[28:29], v[2:3] op_sel_hi:[1,0]
	v_pk_mul_f32 v[26:27], v[26:27], v[2:3] op_sel_hi:[1,0]
	v_pk_mul_f32 v[24:25], v[24:25], v[2:3] op_sel_hi:[1,0]
	v_pk_mul_f32 v[22:23], v[22:23], v[2:3] op_sel_hi:[1,0]
	v_pk_mul_f32 v[20:21], v[20:21], v[2:3] op_sel_hi:[1,0]
	v_pk_mul_f32 v[18:19], v[18:19], v[2:3] op_sel_hi:[1,0]
	v_pk_mul_f32 v[16:17], v[16:17], v[2:3] op_sel_hi:[1,0]

.Lsel_fast:
	v_fmamk_f32 v7, v149, 0x42000000, v1
	v_add_f32_e32 v6, 0, v1
	s_nop 0
	v_fmac_f32_e32 v6, 0x3e38aa3b, v48
	v_mov_b32_e32 v2, v6
	v_fmamk_f32 v4, v149, 0x42040000, v1
	v_fmamk_f32 v5, v149, 0x420c0000, v1
	s_nop 7
	v_fmac_f32_e32 v7, 0x3e38aa3b, v64
	v_mov_b32_e32 v3, v7
	v_cndmask_b32_e64 v6, v194, v3, s[68:69]
	v_add_f32_e32 v3, v149, v1
	v_fmac_f32_e32 v3, 0x3e38aa3b, v49
	v_fmac_f32_e32 v4, 0x3e38aa3b, v65
	v_cndmask_b32_e64 v7, v194, v2, s[68:69]
	v_cndmask_b32_e64 v9, v194, v3, s[68:69]
	v_cndmask_b32_e64 v8, v194, v4, s[68:69]
	v_max_f32_e32 v2, v7, v6
	v_max_f32_e32 v3, v9, v8
	v_max3_f32 v2, v2, s4, v3
	v_fma_f32 v3, 2.0, v149, v1
	v_fmac_f32_e32 v3, 0x3e38aa3b, v50
	v_fmamk_f32 v4, v149, 0x42080000, v1
	v_fmac_f32_e32 v4, 0x3e38aa3b, v66
	v_cndmask_b32_e64 v10, v194, v4, s[68:69]
	v_fmamk_f32 v4, v149, 0x40400000, v1
	v_readlane_b32 s4, v254, 17
	v_fmac_f32_e32 v4, 0x3e38aa3b, v51
	v_readlane_b32 s5, v254, 18
	v_fmac_f32_e32 v5, 0x3e38aa3b, v67
	v_cndmask_b32_e64 v11, v194, v3, s[68:69]
	v_cndmask_b32_e64 v14, v194, v4, s[68:69]
	v_cndmask_b32_e64 v12, v194, v5, s[68:69]
	v_max_f32_e32 v3, v11, v10
	v_max_f32_e32 v4, v14, v12
	v_readlane_b32 s4, v254, 19
	v_max3_f32 v2, v2, v3, v4
	v_fmamk_f32 v3, v149, 0x41000000, v1
	v_readlane_b32 s5, v254, 20
	v_fmac_f32_e32 v3, 0x3e38aa3b, v52
	v_fmamk_f32 v4, v149, 0x42200000, v1
	v_fmac_f32_e32 v4, 0x3e38aa3b, v68
	v_cndmask_b32_e64 v15, v194, v4, s[68:69]
	v_fmamk_f32 v4, v149, 0x41100000, v1
	v_fmac_f32_e32 v4, 0x3e38aa3b, v53
	v_fmamk_f32 v5, v149, 0x42240000, v1
	v_fmac_f32_e32 v5, 0x3e38aa3b, v69
	v_cndmask_b32_e64 v48, v194, v3, s[68:69]
	v_cndmask_b32_e64 v52, v194, v4, s[68:69]
	v_cndmask_b32_e64 v51, v194, v5, s[68:69]
	v_max_f32_e32 v3, v48, v15
	v_max_f32_e32 v4, v52, v51
	v_max3_f32 v2, v2, v3, v4
	v_fmamk_f32 v3, v149, 0x41200000, v1
	v_fmac_f32_e32 v3, 0x3e38aa3b, v54
	v_fmamk_f32 v4, v149, 0x42280000, v1
	v_fmac_f32_e32 v4, 0x3e38aa3b, v70
	v_cndmask_b32_e64 v53, v194, v4, s[68:69]
	v_fmamk_f32 v4, v149, 0x41300000, v1
	v_fmac_f32_e32 v4, 0x3e38aa3b, v55
	v_fmamk_f32 v5, v149, 0x422c0000, v1
	v_fmac_f32_e32 v5, 0x3e38aa3b, v71
	v_cndmask_b32_e64 v54, v194, v3, s[68:69]
	v_cndmask_b32_e64 v65, v194, v4, s[68:69]
	v_cndmask_b32_e64 v64, v194, v5, s[68:69]
	v_max_f32_e32 v3, v54, v53
	v_max_f32_e32 v4, v65, v64
	v_max3_f32 v2, v2, v3, v4
	v_fmamk_f32 v3, v149, 0x41800000, v1
	v_fmac_f32_e32 v3, 0x3e38aa3b, v56
	v_fmamk_f32 v4, v149, 0x42400000, v1
	v_fmac_f32_e32 v4, 0x3e38aa3b, v72
	v_cndmask_b32_e64 v66, v194, v4, s[68:69]
	v_fmamk_f32 v4, v149, 0x41880000, v1
	v_fmac_f32_e32 v4, 0x3e38aa3b, v57
	v_fmamk_f32 v5, v149, 0x42440000, v1
	v_fmac_f32_e32 v5, 0x3e38aa3b, v73
	v_cndmask_b32_e64 v67, v194, v3, s[68:69]
	v_cndmask_b32_e64 v68, v194, v4, s[68:69]
	v_cndmask_b32_e64 v57, v194, v5, s[68:69]
	v_max_f32_e32 v3, v67, v66
	v_max_f32_e32 v4, v68, v57
	v_max3_f32 v2, v2, v3, v4
	v_fmamk_f32 v3, v149, 0x41900000, v1
	v_fmac_f32_e32 v3, 0x3e38aa3b, v58
	v_fmamk_f32 v4, v149, 0x42480000, v1
	v_fmac_f32_e32 v4, 0x3e38aa3b, v74
	v_cndmask_b32_e64 v58, v194, v4, s[68:69]
	v_fmamk_f32 v4, v149, 0x41980000, v1
	v_fmac_f32_e32 v4, 0x3e38aa3b, v59
	v_fmamk_f32 v5, v149, 0x424c0000, v1
	v_fmac_f32_e32 v5, 0x3e38aa3b, v75
	v_cndmask_b32_e64 v69, v194, v3, s[68:69]
	v_cndmask_b32_e64 v59, v194, v4, s[68:69]
	v_cndmask_b32_e64 v49, v194, v5, s[68:69]
	v_max_f32_e32 v3, v69, v58
	v_max_f32_e32 v4, v59, v49
	v_max3_f32 v2, v2, v3, v4
	v_fmamk_f32 v3, v149, 0x41c00000, v1
	v_fmac_f32_e32 v3, 0x3e38aa3b, v60
	v_fmamk_f32 v4, v149, 0x42600000, v1
	v_fmac_f32_e32 v4, 0x3e38aa3b, v76
	v_cndmask_b32_e64 v13, v194, v3, s[68:69]
	v_fmamk_f32 v3, v149, 0x41c80000, v1
	v_fmac_f32_e32 v3, 0x3e38aa3b, v61
	v_fmamk_f32 v50, v149, 0x42640000, v1
	v_fmac_f32_e32 v50, 0x3e38aa3b, v77
	v_mov_b32_e32 v55, v50
	v_cndmask_b32_e64 v4, v194, v4, s[68:69]
	v_cndmask_b32_e64 v50, v194, v3, s[68:69]
	v_cndmask_b32_e64 v3, v194, v55, s[68:69]
	v_max_f32_e32 v5, v13, v4
	v_max_f32_e32 v55, v50, v3
	v_max3_f32 v2, v2, v5, v55
	v_fmamk_f32 v5, v149, 0x41d00000, v1
	v_fmac_f32_e32 v5, 0x3e38aa3b, v62
	v_fmamk_f32 v55, v149, 0x42680000, v1
	v_fmac_f32_e32 v55, 0x3e38aa3b, v78
	v_mov_b32_e32 v56, v55
	v_cndmask_b32_e64 v55, v194, v5, s[68:69]
	v_cndmask_b32_e64 v5, v194, v56, s[68:69]
	v_fmamk_f32 v56, v149, 0x41d80000, v1
	v_fmac_f32_e32 v56, 0x3e38aa3b, v63
	v_fmac_f32_e32 v1, 0x426c0000, v149
	v_fmac_f32_e32 v1, 0x3e38aa3b, v79
	v_cndmask_b32_e64 v56, v194, v56, s[68:69]
	v_cndmask_b32_e64 v1, v194, v1, s[68:69]
	s_branch .Lsel_join

.LBB0_850:
	s_nop 10
	v_mov_b32_e32 v166, v105
	s_andn2_b64 vcc, exec, s[70:71]
	s_cbranch_vccz .LBB0_841
	s_branch .LBB0_842
.LBB0_851:
	s_movk_i32 s86, 0x1000
	v_readlane_b32 s87, v253, 56
	v_readlane_b32 s41, v254, 25
	s_nop 7
	v_mov_b64_e32 v[48:49], v[16:17]
	v_mov_b64_e32 v[50:51], v[18:19]
	v_mov_b64_e32 v[52:53], v[20:21]
	v_mov_b64_e32 v[54:55], v[22:23]
	v_mov_b64_e32 v[56:57], v[24:25]
	v_mov_b64_e32 v[58:59], v[26:27]
	v_mov_b64_e32 v[60:61], v[28:29]
	v_mov_b64_e32 v[62:63], v[30:31]
	v_mov_b64_e32 v[64:65], v[32:33]
	v_mov_b64_e32 v[66:67], v[34:35]
	v_mov_b64_e32 v[68:69], v[36:37]
	v_mov_b64_e32 v[70:71], v[38:39]
	v_mov_b64_e32 v[72:73], v[40:41]
	v_mov_b64_e32 v[74:75], v[42:43]
	v_mov_b64_e32 v[76:77], v[44:45]
	v_mov_b64_e32 v[78:79], v[46:47]
	s_branch .LBB0_853
